# prologue weight conversion: per-segment rotation of the wave->item dealing so item counts per wave are balanced (37 vs 44 max); on top of norm rewrite + K-loop barrier handoff
# speedup vs baseline: 1.0043x; 1.0043x over previous
; #define LAS __attribute__((address_space(3)))
; __device__ __forceinline__ void convert_segments(const Args& args, unsigned char* ws, LAS unsigned char* lds, int seg_lo, int seg_hi, int part_lo, int part_hi, int nparts, int wid, int nw, int wave, int lane) {
;     LAS float* scr = (LAS float*)(lds + wave * 16640);
; #pragma unroll 1
;     for (int sI = seg_lo; sI < seg_hi; ++sI) {
;         const Seg sg = seg_at(sI);
;         const int nblk = sg.ncols / 64, nit = (sg.K / 64) * nblk;
;         const float* W = args.in[sg.in_idx] + (size_t)sg.src_l * sg.K * sg.N;
;         bf16* WT = (bf16*)(ws + WS_W + (size_t)sg.layer * LAYER_W + (size_t)sg.wsub_mib * MiB);
;         const int it_lo = (int)((long)nit * part_lo / nparts), it_hi = (int)((long)nit * part_hi / nparts);
;         int it = it_lo + wid;
;         f32x4 v[16];
.LBB0_11:
	s_or_b64 exec, exec, s[4:5]
	s_load_dwordx2 s[36:37], s[0:1], 0xf0
	v_readlane_b32 s4, v254, 0
	s_lshr_b32 s89, s3, 6
	s_lshl_b32 s4, s4, 3
	s_lshl_b32 s38, s88, 3
	s_add_i32 s40, s4, s89
	s_waitcnt lgkmcnt(0)
	s_cmp_lt_i32 s36, 1
	s_cselect_b64 s[4:5], -1, 0
	s_cmp_gt_i32 s37, 0
	s_cselect_b64 s[6:7], -1, 0
	s_and_b64 s[4:5], s[4:5], s[6:7]
	s_andn2_b64 vcc, exec, s[4:5]
	s_cbranch_vccnz .LBB0_49
	s_mov_b64 s[12:13], 0
	s_load_dwordx2 s[14:15], s[0:1], 0xe8
	s_mul_i32 s4, s89, 0x4100
	v_mbcnt_lo_u32_b32 v65, -1, 0
	v_mbcnt_hi_u32_b32 v65, -1, v65
	s_mov_b32 s21, 0
	v_lshlrev_b32_e32 v0, 3, v65
	s_waitcnt lgkmcnt(0)
	s_add_u32 s5, s14, s12
	s_addc_u32 s6, s15, s13
	s_cmpk_eq_i32 s88, 0x100
	s_cselect_b32 s19, 23, 26
	s_add_i32 s4, s4, 0
	s_add_u32 s24, s5, 0x2d400000
	v_ashrrev_i32_e32 v66, 4, v65
	v_lshlrev_b32_e32 v64, 2, v65
	s_movk_i32 s5, 0x104
	v_ashrrev_i32_e32 v102, 3, v65
	v_and_b32_e32 v0, 56, v0
	v_and_b32_e32 v68, 60, v64
	v_mul_lo_u32 v2, v66, s5
	v_mul_u32_u24_e32 v3, 0x104, v0
	v_lshlrev_b32_e32 v4, 2, v102
	v_readlane_b32 s5, v254, 0
	s_addc_u32 s25, s6, 0
	v_lshl_add_u32 v1, v68, 2, s4
	v_add3_u32 v67, s4, v3, v4
	s_lshl_b32 s27, s5, 9
	s_lshl_b32 s4, s89, 6
	s_add_i32 s27, s27, s4
	s_lshl_b32 s39, s5, 10
	s_lshl_b32 s4, s89, 7
	v_mov_b32_e32 v71, 0
	v_add_u32_e32 v72, 4, v66
	v_add_u32_e32 v74, 8, v66
	v_add_u32_e32 v76, 12, v66
	v_add_u32_e32 v78, 16, v66
	v_add_u32_e32 v80, 20, v66
	v_add_u32_e32 v82, 24, v66
	v_add_u32_e32 v84, 28, v66
	v_add_u32_e32 v86, 32, v66
	v_add_u32_e32 v88, 36, v66
	v_add_u32_e32 v90, 40, v66
	v_add_u32_e32 v92, 44, v66
	v_add_u32_e32 v94, 48, v66
	v_add_u32_e32 v96, 52, v66
	v_add_u32_e32 v98, 56, v66
	v_add_u32_e32 v100, 60, v66
	v_add_u32_e32 v104, 8, v102
	v_add_u32_e32 v106, 16, v102
	v_add_u32_e32 v108, 24, v102
	v_add_u32_e32 v110, 32, v102
	v_add_u32_e32 v112, 40, v102
	v_add_u32_e32 v114, 48, v102
	v_add_u32_e32 v116, 56, v102
	s_ashr_i32 s41, s40, 31
	s_abs_i32 s26, s40
	s_lshl_b32 s18, s88, 9
	s_add_i32 s39, s39, s4
	s_lshl_b32 s42, s88, 10
	v_add_u32_e32 v69, v1, v2
	v_lshlrev_b32_e32 v70, 1, v0
	s_mov_b32 s43, 0
	s_mov_b32 s99, 0
	s_branch .LBB0_14

; __device__ __forceinline__ void convert_segments(const Args& args, unsigned char* ws, LAS unsigned char* lds, int seg_lo, int seg_hi, int part_lo, int part_hi, int nparts, int wid, int nw, int wave, int lane) {
;     ...
;     for (int sI = seg_lo; sI < seg_hi; ++sI) {
;         const Seg sg = seg_at(sI);
;         const int nblk = sg.ncols / 64, nit = (sg.K / 64) * nblk;
;         const float* W = args.in[sg.in_idx] + (size_t)sg.src_l * sg.K * sg.N;
;         bf16* WT = (bf16*)(ws + WS_W + (size_t)sg.layer * LAYER_W + (size_t)sg.wsub_mib * MiB);
;         const int it_lo = (int)((long)nit * part_lo / nparts), it_hi = (int)((long)nit * part_hi / nparts);
;         int it = it_lo + wid;
;         f32x4 v[16];
;         if (it < it_hi) { const int kb = it / nblk, nb = it - kb * nblk; tr_load(W + (size_t)(64 * kb) * sg.N + sg.scol + 64 * nb, sg.N, v, lane); }
; #pragma unroll 1
;         for (; it < it_hi; it += nw) {
;             const int kb = it / nblk, nb = it - kb * nblk;
;             const int drow = sg.ilv ? (256 * (nb >> 1) + 64 * (nb & 1) + sg.drow) : (sg.drow + 64 * nb);
;             tr_to_lds(v, scr, lane);
;             const int itn = it + nw;
;             if (itn < it_hi) { const int kbn = itn / nblk, nbn = itn - kbn * nblk; tr_load(W + (size_t)(64 * kbn) * sg.N + sg.scol + 64 * nbn, sg.N, v, lane); }
.LBB0_14:
	s_mul_i32 s7, s43, 40
	s_getpc_b64 s[4:5]
	s_add_u32 s4, s4, __const._Z6seg_ati.segs@rel32@lo+4
	s_addc_u32 s5, s5, __const._Z6seg_ati.segs@rel32@hi+12
	s_mul_hi_u32 s6, s43, 40
	s_add_u32 s22, s4, s7
	s_addc_u32 s23, s5, s6
	s_load_dwordx8 s[4:11], s[22:23], 0x0
	v_lshlrev_b32_e32 v118, 2, v68
	s_waitcnt lgkmcnt(0)
	s_ashr_i32 s20, s9, 31
	s_ashr_i32 s48, s7, 31
	s_lshr_b32 s20, s20, 26
	s_lshr_b32 s44, s48, 26
	s_add_i32 s9, s9, s20
	s_ashr_i32 s51, s9, 6
	s_add_i32 s9, s7, s44
	s_ashr_i32 s47, s4, 31
	s_mov_b32 s46, s4
	s_ashr_i32 s9, s9, 6
	s_lshl_b64 s[46:47], s[46:47], 3
	s_add_u32 s46, s0, s46
	s_addc_u32 s47, s1, s47
	s_mul_i32 s44, s51, s9
	s_load_dwordx2 s[46:47], s[46:47], 0x0
	s_mul_i32 s9, s6, s5
	s_mul_hi_i32 s4, s6, s5
	s_mul_i32 s5, s9, s48
	s_mul_hi_u32 s20, s9, s7
	s_add_i32 s5, s20, s5
	s_mul_i32 s4, s4, s7
	s_add_i32 s5, s5, s4
	s_mul_i32 s4, s9, s7
	s_lshl_b64 s[4:5], s[4:5], 2
	s_waitcnt lgkmcnt(0)
	s_add_u32 s46, s46, s4
	s_addc_u32 s47, s47, s5
	s_add_i32 s98, s40, s99
	s_cmp_ge_u32 s98, s38
	s_cselect_b32 s100, s38, 0
	s_sub_i32 s98, s98, s100
	s_cmpk_eq_i32 s88, 0x100
	s_cselect_b32 s100, 0x7ff, 0
	s_sub_i32 s99, s99, s44
	s_and_b32 s99, s99, s100
	s_cmp_lt_i32 s98, s44
	s_mov_b32 s45, s7
	s_cselect_b64 s[4:5], -1, 0
	s_cmp_ge_i32 s98, s44
	s_cbranch_scc1 .LBB0_16
	s_abs_i32 s7, s51
	s_waitcnt vmcnt(15)
	v_cvt_f32_u32_e32 v0, s7
	s_sub_i32 s20, 0, s7
	s_ashr_i32 s9, s51, 31
	s_xor_b32 s9, s41, s9
	v_rcp_iflag_f32_e32 v0, v0
	v_mov_b32_e32 v119, v71
	v_mul_f32_e32 v0, 0x4f7ffffe, v0
	v_cvt_u32_f32_e32 v0, v0
	s_nop 0
	v_readfirstlane_b32 s48, v0
	s_mul_i32 s20, s20, s48
	s_mul_hi_u32 s20, s48, s20
	s_add_i32 s48, s48, s20
	s_mul_hi_u32 s20, s98, s48
	s_mul_i32 s48, s20, s7
	s_sub_i32 s48, s98, s48
	s_add_i32 s49, s20, 1
	s_sub_i32 s50, s48, s7
	s_cmp_ge_u32 s48, s7
	s_cselect_b32 s20, s49, s20
	s_cselect_b32 s48, s50, s48
	s_add_i32 s49, s20, 1
	s_cmp_ge_u32 s48, s7
	s_cselect_b32 s7, s49, s20
	s_xor_b32 s7, s7, s9
	s_sub_i32 s7, s7, s9
	s_mul_i32 s9, s7, s51
	s_lshl_b32 s7, s7, 6
	s_mul_hi_i32 s49, s7, s6
	s_mul_i32 s48, s7, s6
	s_sub_i32 s20, s98, s9
	s_lshl_b64 s[48:49], s[48:49], 2
	s_add_u32 s7, s46, s48
	s_addc_u32 s50, s47, s49
	s_ashr_i32 s9, s8, 31
	s_lshl_b64 s[48:49], s[8:9], 2
	s_add_u32 s7, s7, s48
	s_addc_u32 s9, s50, s49
	s_lshl_b32 s48, s20, 6
	s_ashr_i32 s49, s48, 31
	s_lshl_b64 s[48:49], s[48:49], 2
	s_add_u32 s48, s7, s48
	s_addc_u32 s49, s9, s49
	s_waitcnt vmcnt(5)
	v_lshl_add_u64 v[40:41], s[48:49], 0, v[118:119]
	v_mad_i64_i32 v[0:1], s[48:49], s6, v66, 0
	s_waitcnt vmcnt(4)
	v_mad_i64_i32 v[44:45], s[48:49], s6, v92, 0
	v_lshl_add_u64 v[8:9], v[0:1], 2, v[40:41]
	v_mad_i64_i32 v[0:1], s[48:49], s6, v72, 0
	v_lshl_add_u64 v[120:121], v[44:45], 2, v[40:41]
	v_mad_i64_i32 v[44:45], s[48:49], s6, v94, 0
	v_lshl_add_u64 v[10:11], v[0:1], 2, v[40:41]
	v_lshl_add_u64 v[122:123], v[44:45], 2, v[40:41]
	v_mad_i64_i32 v[44:45], s[48:49], s6, v96, 0
	global_load_dwordx4 v[0:3], v[8:9], off
	global_load_dwordx4 v[4:7], v[10:11], off
	v_mad_i64_i32 v[8:9], s[48:49], s6, v74, 0
	v_mad_i64_i32 v[10:11], s[48:49], s6, v76, 0
	v_mad_i64_i32 v[16:17], s[48:49], s6, v78, 0
	v_mad_i64_i32 v[18:19], s[48:49], s6, v80, 0
	v_mad_i64_i32 v[24:25], s[48:49], s6, v82, 0
	v_mad_i64_i32 v[26:27], s[48:49], s6, v84, 0
	v_mad_i64_i32 v[32:33], s[48:49], s6, v86, 0
	v_mad_i64_i32 v[34:35], s[48:49], s6, v88, 0
	v_mad_i64_i32 v[42:43], s[48:49], s6, v90, 0
	v_lshl_add_u64 v[124:125], v[44:45], 2, v[40:41]
	v_mad_i64_i32 v[44:45], s[48:49], s6, v98, 0
	v_lshl_add_u64 v[8:9], v[8:9], 2, v[40:41]
	v_lshl_add_u64 v[12:13], v[10:11], 2, v[40:41]
	v_lshl_add_u64 v[16:17], v[16:17], 2, v[40:41]
	v_lshl_add_u64 v[20:21], v[18:19], 2, v[40:41]
	v_lshl_add_u64 v[24:25], v[24:25], 2, v[40:41]
	v_lshl_add_u64 v[28:29], v[26:27], 2, v[40:41]
	v_lshl_add_u64 v[32:33], v[32:33], 2, v[40:41]
	v_lshl_add_u64 v[36:37], v[34:35], 2, v[40:41]
	v_lshl_add_u64 v[42:43], v[42:43], 2, v[40:41]
	v_lshl_add_u64 v[126:127], v[44:45], 2, v[40:41]
	v_mad_i64_i32 v[44:45], s[48:49], s6, v100, 0
	global_load_dwordx4 v[8:11], v[8:9], off
	s_nop 0
	global_load_dwordx4 v[12:15], v[12:13], off
	s_nop 0
	global_load_dwordx4 v[16:19], v[16:17], off
	s_nop 0
	global_load_dwordx4 v[20:23], v[20:21], off
	s_nop 0
	global_load_dwordx4 v[24:27], v[24:25], off
	s_nop 0
	global_load_dwordx4 v[28:31], v[28:29], off
	s_nop 0
	global_load_dwordx4 v[32:35], v[32:33], off
	s_nop 0
	global_load_dwordx4 v[36:39], v[36:37], off
	v_lshl_add_u64 v[128:129], v[44:45], 2, v[40:41]
	global_load_dwordx4 v[40:43], v[42:43], off
	s_nop 0
	global_load_dwordx4 v[44:47], v[120:121], off
	global_load_dwordx4 v[48:51], v[122:123], off
	global_load_dwordx4 v[52:55], v[124:125], off
	global_load_dwordx4 v[56:59], v[126:127], off
	global_load_dwordx4 v[60:63], v[128:129], off
.LBB0_16:
	s_andn2_b64 vcc, exec, s[4:5]
	s_cbranch_vccnz .LBB0_13
	s_mul_i32 s5, s10, 0x1a400000
	s_mul_hi_i32 s4, s10, 0x1a400000
	s_add_u32 s9, s24, s5
	s_addc_u32 s10, s25, s4
	s_ashr_i32 s5, s11, 31
	s_mov_b32 s4, s11
	s_lshl_b64 s[4:5], s[4:5], 20
	s_load_dword s7, s[22:23], 0x20
	s_add_u32 s22, s9, s4
	s_addc_u32 s23, s10, s5
	s_lshl_b64 s[4:5], 1, s43
	s_and_b32 s20, s4, 0x27f9fff
	s_cmp_lg_u64 s[20:21], 0
	s_cselect_b64 s[4:5], -1, 0
	s_ashr_i32 s9, s8, 31
	s_lshl_b64 s[8:9], s[8:9], 2
	s_add_u32 s20, s46, s8
	s_addc_u32 s46, s47, s9
	s_abs_i32 s47, s51
	v_cvt_f32_u32_e32 v73, s47
	v_mad_i64_i32 v[120:121], s[8:9], s6, v66, 0
	v_mad_i64_i32 v[122:123], s[8:9], s6, v72, 0
	v_rcp_iflag_f32_e32 v73, v73
	v_mad_i64_i32 v[124:125], s[8:9], s6, v74, 0
	v_mad_i64_i32 v[126:127], s[8:9], s6, v76, 0
	v_mul_f32_e32 v73, 0x4f7ffffe, v73
	v_cvt_u32_f32_e32 v73, v73
	v_mad_i64_i32 v[128:129], s[8:9], s6, v78, 0
	v_mad_i64_i32 v[130:131], s[8:9], s6, v80, 0
	v_mad_i64_i32 v[132:133], s[8:9], s6, v82, 0
	v_mad_i64_i32 v[134:135], s[8:9], s6, v84, 0
	v_mad_i64_i32 v[136:137], s[8:9], s6, v86, 0
	v_mad_i64_i32 v[138:139], s[8:9], s6, v88, 0
	v_mad_i64_i32 v[140:141], s[8:9], s6, v90, 0
	v_mad_i64_i32 v[142:143], s[8:9], s6, v92, 0
	v_mad_i64_i32 v[144:145], s[8:9], s6, v94, 0
	v_mad_i64_i32 v[146:147], s[8:9], s6, v96, 0
	v_mad_i64_i32 v[148:149], s[8:9], s6, v98, 0
	v_mad_i64_i32 v[150:151], s[8:9], s6, v100, 0
	v_mad_i64_i32 v[152:153], s[8:9], s45, v102, 0
	v_mad_i64_i32 v[154:155], s[8:9], s45, v104, 0
	v_mad_i64_i32 v[156:157], s[8:9], s45, v106, 0
	v_mad_i64_i32 v[158:159], s[8:9], s45, v108, 0
	v_mad_i64_i32 v[160:161], s[8:9], s45, v110, 0
	v_mad_i64_i32 v[162:163], s[8:9], s45, v112, 0
	v_mad_i64_i32 v[164:165], s[8:9], s45, v114, 0
	v_mad_i64_i32 v[166:167], s[8:9], s45, v116, 0
	s_sub_i32 s8, 0, s47
	v_readfirstlane_b32 s9, v73
	s_mul_i32 s8, s8, s9
	s_mul_hi_u32 s8, s9, s8
	s_add_i32 s49, s9, s8
	s_lshl_b32 s8, s51, 6
	s_sub_i32 s50, 0, s8
	s_lshl_b32 s8, s51, 7
	s_ashr_i32 s48, s51, 31
	s_sub_i32 s51, 0, s8
	s_lshl_b32 s52, s98, 7
	s_lshl_b32 s56, s98, 6
	s_mov_b32 s53, s98
